# v2 + RWKV S1 phase: second GEMM unit-to-workgroup map shifted by -64 so no workgroup gets 3+1 units (max 5 -> 4 unit-equivalents)
# speedup vs baseline: 1.0129x; 1.0129x over previous
.LBB0_1160:
	s_cmp_eq_u32 s85, 7
	s_cbranch_scc0 .Lmy_s1_norestore
	s_cmp_eq_u32 s57, 1
	s_cbranch_scc0 .Lmy_s1_norestore
	s_add_i32 s2, s2, 0x40
	s_and_b32 s2, s2, 0xff
	s_lshr_b32 vcc_lo, s2, 3
	v_writelane_b32 v252, vcc_lo, 40
	s_and_b32 vcc_lo, s2, 7
	v_writelane_b32 v252, vcc_lo, 43

.LBB0_1171:
	s_cmp_eq_u32 s85, 7
	s_cbranch_scc0 .Lmy_s1_noshift
	s_cmp_eq_u32 s57, 1
	s_cbranch_scc0 .Lmy_s1_noshift
	s_add_i32 s2, s2, 0xc0
	s_and_b32 s2, s2, 0xff
	s_lshr_b32 vcc_lo, s2, 3
	v_writelane_b32 v252, vcc_lo, 40
	s_and_b32 vcc_lo, s2, 7
	v_writelane_b32 v252, vcc_lo, 43
